# P5 NSA work queues: on leaving its own queue a wave reads all eight counters once (eight sc1 loads in flight) and skips empty queues while stealing instead of one failed returning atomic per empty que
# speedup vs baseline: 1.0083x; 1.0083x over previous
.Lpk_next:
	s_cmp_eq_u32 s94, 8
	s_cbranch_scc1 .LBB0_403
	s_cmp_lg_u32 s94, 1
	s_cbranch_scc1 .Lpk_have
	v_mov_b32_e32 v232, 0
	global_load_dword v233, v232, s[68:69] offset:128 sc1
	global_load_dword v234, v232, s[68:69] offset:256 sc1
	global_load_dword v235, v232, s[68:69] offset:384 sc1
	global_load_dword v236, v232, s[68:69] offset:512 sc1
	global_load_dword v237, v232, s[68:69] offset:640 sc1
	global_load_dword v238, v232, s[68:69] offset:768 sc1
	global_load_dword v239, v232, s[68:69] offset:896 sc1
	global_load_dword v240, v232, s[68:69] offset:1024 sc1
	s_waitcnt vmcnt(0)
	s_mov_b32 s100, 0
	v_readfirstlane_b32 s0, v233
	s_cmpk_lt_u32 s0, 0x200
	s_cselect_b32 s0, 1, 0
	s_or_b32 s100, s100, s0
	v_readfirstlane_b32 s0, v234
	s_cmpk_lt_u32 s0, 0x200
	s_cselect_b32 s0, 2, 0
	s_or_b32 s100, s100, s0
	v_readfirstlane_b32 s0, v235
	s_cmpk_lt_u32 s0, 0x200
	s_cselect_b32 s0, 4, 0
	s_or_b32 s100, s100, s0
	v_readfirstlane_b32 s0, v236
	s_cmpk_lt_u32 s0, 0x200
	s_cselect_b32 s0, 8, 0
	s_or_b32 s100, s100, s0
	v_readfirstlane_b32 s0, v237
	s_cmpk_lt_u32 s0, 0x200
	s_cselect_b32 s0, 16, 0
	s_or_b32 s100, s100, s0
	v_readfirstlane_b32 s0, v238
	s_cmpk_lt_u32 s0, 0x200
	s_cselect_b32 s0, 32, 0
	s_or_b32 s100, s100, s0
	v_readfirstlane_b32 s0, v239
	s_cmpk_lt_u32 s0, 0x200
	s_cselect_b32 s0, 64, 0
	s_or_b32 s100, s100, s0
	v_readfirstlane_b32 s0, v240
	s_cmpk_lt_u32 s0, 0x200
	s_cselect_b32 s0, 128, 0
	s_or_b32 s100, s100, s0
.Lpk_have:
	s_add_i32 s0, s94, s2
	s_and_b32 s0, s0, 7
	s_lshr_b32 s1, s100, s0
	s_bitcmp1_b32 s1, 0
	s_cbranch_scc1 .LBB0_368
	s_add_i32 s94, s94, 1
	s_add_i32 s93, s93, 1
	s_branch .Lpk_next
